# waves 4-7 run their whole merged-stage block (reads, MFMAs, ISSUE, solve) at s_setprio 3
# speedup vs baseline: 1.0050x; 1.0050x over previous
.Lsx0_a:
.Lsx0_c:
	s_and_saveexec_b64 s[2:3], s[56:57]
	s_cbranch_execz .LBB0_403
	s_setprio 3
	ds_read_b128 v[48:51], v174
	ds_read_b128 v[60:63], v192 offset:49152
	ds_read_b128 v[52:55], v174 offset:64
	ds_read_b128 v[64:67], v192 offset:49216
	ds_read_b128 v[56:59], v175
	ds_read_b128 v[68:71], v199
	ds_read_b128 v[72:75], v192 offset:58368
	ds_read_b128 v[76:79], v192 offset:58432
	ds_read_b128 v[80:83], v151
	ds_read_b128 v[84:87], v151 offset:16
	ds_read_b128 v[88:91], v151 offset:32
	ds_read_b128 v[92:95], v151 offset:48
	s_waitcnt lgkmcnt(10)
	v_mfma_f32_16x16x32_bf16 v[30:33], v[48:51], v[60:63], 0
	s_waitcnt lgkmcnt(8)
	v_mfma_f32_16x16x32_bf16 v[30:33], v[52:55], v[64:67], v[30:33]
	s_waitcnt lgkmcnt(6)
	v_mfma_f32_16x16x32_bf16 v[30:33], v[56:59], v[68:71], v[30:33]
	s_waitcnt lgkmcnt(5)
	v_mfma_f32_16x16x32_bf16 v[22:25], v[48:51], v[72:75], 0
	s_waitcnt lgkmcnt(4)
	v_mfma_f32_16x16x32_bf16 v[22:25], v[52:55], v[76:79], v[22:25]
	s_cmp_eq_u32 s36, 0
	s_cbranch_scc1 .Lis0b
	s_cmp_gt_u32 s36, 62
	s_cbranch_scc1 .Lis0b
	s_add_i32 s24, s19, 0xffffffc0
	s_add_i32 s25, s21, 0x30
	s_and_b64 s[98:99], s[12:13], exec
	s_cselect_b32 s24, s25, s24
	v_lshl_add_u32 v194, s24, 6, v183
	v_lshlrev_b32_e32 v112, 1, v194
	global_load_dword v5, v112, s[44:45]
	global_load_dword v207, v112, s[44:45] offset:-1024
	global_load_dword v6, v112, s[42:43]
	global_load_dword v208, v112, s[42:43] offset:-1024
	global_load_dword v7, v112, s[0:1]
	global_load_dword v209, v112, s[0:1] offset:-1024
	global_load_dword v8, v112, s[34:35]
	global_load_dword v210, v112, s[34:35] offset:-1024
	global_load_dword v9, v112, s[76:77]
	global_load_dword v211, v112, s[76:77] offset:-1024
	v_add_u32_e32 v194, s24, v184
	v_lshlrev_b32_e32 v114, 2, v194
	global_load_dword v110, v114, s[40:41]
	global_load_dword v212, v114, s[40:41] offset:-32

.Lsx0_d:
	v_lshrrev_b32_e32 v96, 6, v198
	v_mul_u32_u24_e32 v96, 0x500, v96
	v_mad_u32_u24 v96, v145, 20, v96
	v_and_b32_e32 v97, 15, v198
	v_lshl_add_u32 v96, v97, 1, v96
	v_add_u32_e32 v96, 0x10a00, v96
	s_waitcnt lgkmcnt(0)
	s_nop 1
	v_fmac_f32_dpp v30, v30, v80 row_newbcast:0 row_mask:0xf bank_mask:0xf
	v_fmac_f32_dpp v31, v31, v80 row_newbcast:0 row_mask:0xf bank_mask:0xf
	v_fmac_f32_dpp v32, v32, v80 row_newbcast:0 row_mask:0xf bank_mask:0xf
	v_fmac_f32_dpp v33, v33, v80 row_newbcast:0 row_mask:0xf bank_mask:0xf
	v_fmac_f32_dpp v30, v30, v81 row_newbcast:1 row_mask:0xf bank_mask:0xf
	v_fmac_f32_dpp v31, v31, v81 row_newbcast:1 row_mask:0xf bank_mask:0xf
	v_fmac_f32_dpp v32, v32, v81 row_newbcast:1 row_mask:0xf bank_mask:0xf
	v_fmac_f32_dpp v33, v33, v81 row_newbcast:1 row_mask:0xf bank_mask:0xf
	v_fmac_f32_dpp v30, v30, v82 row_newbcast:2 row_mask:0xf bank_mask:0xf
	v_fmac_f32_dpp v31, v31, v82 row_newbcast:2 row_mask:0xf bank_mask:0xf
	v_fmac_f32_dpp v32, v32, v82 row_newbcast:2 row_mask:0xf bank_mask:0xf
	v_fmac_f32_dpp v33, v33, v82 row_newbcast:2 row_mask:0xf bank_mask:0xf
	v_fmac_f32_dpp v30, v30, v83 row_newbcast:3 row_mask:0xf bank_mask:0xf
	v_fmac_f32_dpp v31, v31, v83 row_newbcast:3 row_mask:0xf bank_mask:0xf
	v_fmac_f32_dpp v32, v32, v83 row_newbcast:3 row_mask:0xf bank_mask:0xf
	v_fmac_f32_dpp v33, v33, v83 row_newbcast:3 row_mask:0xf bank_mask:0xf
	v_fmac_f32_dpp v30, v30, v84 row_newbcast:4 row_mask:0xf bank_mask:0xf
	v_fmac_f32_dpp v31, v31, v84 row_newbcast:4 row_mask:0xf bank_mask:0xf
	v_fmac_f32_dpp v32, v32, v84 row_newbcast:4 row_mask:0xf bank_mask:0xf
	v_fmac_f32_dpp v33, v33, v84 row_newbcast:4 row_mask:0xf bank_mask:0xf
	v_fmac_f32_dpp v30, v30, v85 row_newbcast:5 row_mask:0xf bank_mask:0xf
	v_fmac_f32_dpp v31, v31, v85 row_newbcast:5 row_mask:0xf bank_mask:0xf
	v_fmac_f32_dpp v32, v32, v85 row_newbcast:5 row_mask:0xf bank_mask:0xf
	v_fmac_f32_dpp v33, v33, v85 row_newbcast:5 row_mask:0xf bank_mask:0xf
	v_fmac_f32_dpp v30, v30, v86 row_newbcast:6 row_mask:0xf bank_mask:0xf
	v_fmac_f32_dpp v31, v31, v86 row_newbcast:6 row_mask:0xf bank_mask:0xf
	v_fmac_f32_dpp v32, v32, v86 row_newbcast:6 row_mask:0xf bank_mask:0xf
	v_fmac_f32_dpp v33, v33, v86 row_newbcast:6 row_mask:0xf bank_mask:0xf
	v_fmac_f32_dpp v30, v30, v87 row_newbcast:7 row_mask:0xf bank_mask:0xf
	v_fmac_f32_dpp v31, v31, v87 row_newbcast:7 row_mask:0xf bank_mask:0xf
	v_fmac_f32_dpp v32, v32, v87 row_newbcast:7 row_mask:0xf bank_mask:0xf
	v_fmac_f32_dpp v33, v33, v87 row_newbcast:7 row_mask:0xf bank_mask:0xf
	v_fmac_f32_dpp v30, v30, v88 row_newbcast:8 row_mask:0xf bank_mask:0xf
	v_fmac_f32_dpp v31, v31, v88 row_newbcast:8 row_mask:0xf bank_mask:0xf
	v_fmac_f32_dpp v32, v32, v88 row_newbcast:8 row_mask:0xf bank_mask:0xf
	v_fmac_f32_dpp v33, v33, v88 row_newbcast:8 row_mask:0xf bank_mask:0xf
	v_fmac_f32_dpp v30, v30, v89 row_newbcast:9 row_mask:0xf bank_mask:0xf
	v_fmac_f32_dpp v31, v31, v89 row_newbcast:9 row_mask:0xf bank_mask:0xf
	v_fmac_f32_dpp v32, v32, v89 row_newbcast:9 row_mask:0xf bank_mask:0xf
	v_fmac_f32_dpp v33, v33, v89 row_newbcast:9 row_mask:0xf bank_mask:0xf
	v_fmac_f32_dpp v30, v30, v90 row_newbcast:10 row_mask:0xf bank_mask:0xf
	v_fmac_f32_dpp v31, v31, v90 row_newbcast:10 row_mask:0xf bank_mask:0xf
	v_fmac_f32_dpp v32, v32, v90 row_newbcast:10 row_mask:0xf bank_mask:0xf
	v_fmac_f32_dpp v33, v33, v90 row_newbcast:10 row_mask:0xf bank_mask:0xf
	v_fmac_f32_dpp v30, v30, v91 row_newbcast:11 row_mask:0xf bank_mask:0xf
	v_fmac_f32_dpp v31, v31, v91 row_newbcast:11 row_mask:0xf bank_mask:0xf
	v_fmac_f32_dpp v32, v32, v91 row_newbcast:11 row_mask:0xf bank_mask:0xf
	v_fmac_f32_dpp v33, v33, v91 row_newbcast:11 row_mask:0xf bank_mask:0xf
	v_fmac_f32_dpp v30, v30, v92 row_newbcast:12 row_mask:0xf bank_mask:0xf
	v_fmac_f32_dpp v31, v31, v92 row_newbcast:12 row_mask:0xf bank_mask:0xf
	v_fmac_f32_dpp v32, v32, v92 row_newbcast:12 row_mask:0xf bank_mask:0xf
	v_fmac_f32_dpp v33, v33, v92 row_newbcast:12 row_mask:0xf bank_mask:0xf
	v_fmac_f32_dpp v30, v30, v93 row_newbcast:13 row_mask:0xf bank_mask:0xf
	v_fmac_f32_dpp v31, v31, v93 row_newbcast:13 row_mask:0xf bank_mask:0xf
	v_fmac_f32_dpp v32, v32, v93 row_newbcast:13 row_mask:0xf bank_mask:0xf
	v_fmac_f32_dpp v33, v33, v93 row_newbcast:13 row_mask:0xf bank_mask:0xf
	v_fmac_f32_dpp v30, v30, v94 row_newbcast:14 row_mask:0xf bank_mask:0xf
	v_fmac_f32_dpp v31, v31, v94 row_newbcast:14 row_mask:0xf bank_mask:0xf
	v_fmac_f32_dpp v32, v32, v94 row_newbcast:14 row_mask:0xf bank_mask:0xf
	v_fmac_f32_dpp v33, v33, v94 row_newbcast:14 row_mask:0xf bank_mask:0xf
	v_cvt_pk_bf16_f32 v80, v30, v31
	v_cvt_pk_bf16_f32 v81, v32, v33
	ds_write_b16 v96, v80 offset:0
	ds_write_b16_d16_hi v96, v80 offset:80
	ds_write_b16 v96, v81 offset:160
	ds_write_b16_d16_hi v96, v81 offset:240
	s_setprio 1

.Lsx1_c:
	s_and_saveexec_b64 s[74:75], s[56:57]
	s_cbranch_execz .LBB0_432
	s_setprio 3
	ds_read_b128 v[48:51], v174
	ds_read_b128 v[60:63], v192 offset:51456
	ds_read_b128 v[52:55], v174 offset:64
	ds_read_b128 v[64:67], v192 offset:51520
	ds_read_b128 v[56:59], v175 offset:5120
	ds_read_b128 v[68:71], v199
	ds_read_b128 v[72:75], v192 offset:60672
	ds_read_b128 v[76:79], v192 offset:60736
	ds_read_b128 v[80:83], v151
	ds_read_b128 v[84:87], v151 offset:16
	ds_read_b128 v[88:91], v151 offset:32
	ds_read_b128 v[92:95], v151 offset:48
	s_waitcnt lgkmcnt(10)
	v_mfma_f32_16x16x32_bf16 v[30:33], v[48:51], v[60:63], 0
	s_waitcnt lgkmcnt(8)
	v_mfma_f32_16x16x32_bf16 v[30:33], v[52:55], v[64:67], v[30:33]
	s_waitcnt lgkmcnt(6)
	v_mfma_f32_16x16x32_bf16 v[30:33], v[56:59], v[68:71], v[30:33]
	s_waitcnt lgkmcnt(5)
	v_mfma_f32_16x16x32_bf16 v[22:25], v[48:51], v[72:75], 0
	s_waitcnt lgkmcnt(4)
	v_mfma_f32_16x16x32_bf16 v[22:25], v[52:55], v[76:79], v[22:25]
	s_cmp_gt_u32 s36, 61
	s_cbranch_scc1 .Lis1bw
	s_add_i32 s24, s19, 0xffffffb0
	s_add_i32 s25, s21, 64
	s_and_b64 s[98:99], s[12:13], exec
	s_cselect_b32 s24, s25, s24
	v_lshl_add_u32 v194, s24, 6, v183
	v_lshlrev_b32_e32 v112, 1, v194
	global_load_dword v0, v112, s[44:45]
	global_load_dword v201, v112, s[44:45] offset:-1024
	global_load_dword v1, v112, s[42:43]
	global_load_dword v202, v112, s[42:43] offset:-1024
	global_load_dword v2, v112, s[0:1]
	global_load_dword v203, v112, s[0:1] offset:-1024
	global_load_dword v4, v112, s[76:77]
	global_load_dword v205, v112, s[76:77] offset:-1024
	global_load_dword v3, v112, s[34:35]
	global_load_dword v204, v112, s[34:35] offset:-1024
	v_add_u32_e32 v194, s24, v184
	v_lshlrev_b32_e32 v114, 2, v194
	global_load_dword v108, v114, s[40:41]
	global_load_dword v206, v114, s[40:41] offset:-32
	s_branch .Lis1b

.Lis1b:
	v_cvt_pk_bf16_f32 v240, v236, v237
	global_store_dword v[238:239], v240, off
	v_cvt_pk_bf16_f32 v245, v234, v235
	global_store_dword v[238:239], v245, off offset:-1024
	v_lshrrev_b32_e32 v96, 6, v198
	v_mul_u32_u24_e32 v96, 0x500, v96
	v_mad_u32_u24 v96, v145, 20, v96
	v_and_b32_e32 v97, 15, v198
	v_lshl_add_u32 v96, v97, 1, v96
	v_add_u32_e32 v96, 0x10a00, v96
	s_waitcnt lgkmcnt(0)
	s_nop 1
	v_fmac_f32_dpp v30, v30, v80 row_newbcast:0 row_mask:0xf bank_mask:0xf
	v_fmac_f32_dpp v31, v31, v80 row_newbcast:0 row_mask:0xf bank_mask:0xf
	v_fmac_f32_dpp v32, v32, v80 row_newbcast:0 row_mask:0xf bank_mask:0xf
	v_fmac_f32_dpp v33, v33, v80 row_newbcast:0 row_mask:0xf bank_mask:0xf
	v_fmac_f32_dpp v30, v30, v81 row_newbcast:1 row_mask:0xf bank_mask:0xf
	v_fmac_f32_dpp v31, v31, v81 row_newbcast:1 row_mask:0xf bank_mask:0xf
	v_fmac_f32_dpp v32, v32, v81 row_newbcast:1 row_mask:0xf bank_mask:0xf
	v_fmac_f32_dpp v33, v33, v81 row_newbcast:1 row_mask:0xf bank_mask:0xf
	v_fmac_f32_dpp v30, v30, v82 row_newbcast:2 row_mask:0xf bank_mask:0xf
	v_fmac_f32_dpp v31, v31, v82 row_newbcast:2 row_mask:0xf bank_mask:0xf
	v_fmac_f32_dpp v32, v32, v82 row_newbcast:2 row_mask:0xf bank_mask:0xf
	v_fmac_f32_dpp v33, v33, v82 row_newbcast:2 row_mask:0xf bank_mask:0xf
	v_fmac_f32_dpp v30, v30, v83 row_newbcast:3 row_mask:0xf bank_mask:0xf
	v_fmac_f32_dpp v31, v31, v83 row_newbcast:3 row_mask:0xf bank_mask:0xf
	v_fmac_f32_dpp v32, v32, v83 row_newbcast:3 row_mask:0xf bank_mask:0xf
	v_fmac_f32_dpp v33, v33, v83 row_newbcast:3 row_mask:0xf bank_mask:0xf
	v_fmac_f32_dpp v30, v30, v84 row_newbcast:4 row_mask:0xf bank_mask:0xf
	v_fmac_f32_dpp v31, v31, v84 row_newbcast:4 row_mask:0xf bank_mask:0xf
	v_fmac_f32_dpp v32, v32, v84 row_newbcast:4 row_mask:0xf bank_mask:0xf
	v_fmac_f32_dpp v33, v33, v84 row_newbcast:4 row_mask:0xf bank_mask:0xf
	v_fmac_f32_dpp v30, v30, v85 row_newbcast:5 row_mask:0xf bank_mask:0xf
	v_fmac_f32_dpp v31, v31, v85 row_newbcast:5 row_mask:0xf bank_mask:0xf
	v_fmac_f32_dpp v32, v32, v85 row_newbcast:5 row_mask:0xf bank_mask:0xf
	v_fmac_f32_dpp v33, v33, v85 row_newbcast:5 row_mask:0xf bank_mask:0xf
	v_fmac_f32_dpp v30, v30, v86 row_newbcast:6 row_mask:0xf bank_mask:0xf
	v_fmac_f32_dpp v31, v31, v86 row_newbcast:6 row_mask:0xf bank_mask:0xf
	v_fmac_f32_dpp v32, v32, v86 row_newbcast:6 row_mask:0xf bank_mask:0xf
	v_fmac_f32_dpp v33, v33, v86 row_newbcast:6 row_mask:0xf bank_mask:0xf
	v_fmac_f32_dpp v30, v30, v87 row_newbcast:7 row_mask:0xf bank_mask:0xf
	v_fmac_f32_dpp v31, v31, v87 row_newbcast:7 row_mask:0xf bank_mask:0xf
	v_fmac_f32_dpp v32, v32, v87 row_newbcast:7 row_mask:0xf bank_mask:0xf
	v_fmac_f32_dpp v33, v33, v87 row_newbcast:7 row_mask:0xf bank_mask:0xf
	v_fmac_f32_dpp v30, v30, v88 row_newbcast:8 row_mask:0xf bank_mask:0xf
	v_fmac_f32_dpp v31, v31, v88 row_newbcast:8 row_mask:0xf bank_mask:0xf
	v_fmac_f32_dpp v32, v32, v88 row_newbcast:8 row_mask:0xf bank_mask:0xf
	v_fmac_f32_dpp v33, v33, v88 row_newbcast:8 row_mask:0xf bank_mask:0xf
	v_fmac_f32_dpp v30, v30, v89 row_newbcast:9 row_mask:0xf bank_mask:0xf
	v_fmac_f32_dpp v31, v31, v89 row_newbcast:9 row_mask:0xf bank_mask:0xf
	v_fmac_f32_dpp v32, v32, v89 row_newbcast:9 row_mask:0xf bank_mask:0xf
	v_fmac_f32_dpp v33, v33, v89 row_newbcast:9 row_mask:0xf bank_mask:0xf
	v_fmac_f32_dpp v30, v30, v90 row_newbcast:10 row_mask:0xf bank_mask:0xf
	v_fmac_f32_dpp v31, v31, v90 row_newbcast:10 row_mask:0xf bank_mask:0xf
	v_fmac_f32_dpp v32, v32, v90 row_newbcast:10 row_mask:0xf bank_mask:0xf
	v_fmac_f32_dpp v33, v33, v90 row_newbcast:10 row_mask:0xf bank_mask:0xf
	v_fmac_f32_dpp v30, v30, v91 row_newbcast:11 row_mask:0xf bank_mask:0xf
	v_fmac_f32_dpp v31, v31, v91 row_newbcast:11 row_mask:0xf bank_mask:0xf
	v_fmac_f32_dpp v32, v32, v91 row_newbcast:11 row_mask:0xf bank_mask:0xf
	v_fmac_f32_dpp v33, v33, v91 row_newbcast:11 row_mask:0xf bank_mask:0xf
	v_fmac_f32_dpp v30, v30, v92 row_newbcast:12 row_mask:0xf bank_mask:0xf
	v_fmac_f32_dpp v31, v31, v92 row_newbcast:12 row_mask:0xf bank_mask:0xf
	v_fmac_f32_dpp v32, v32, v92 row_newbcast:12 row_mask:0xf bank_mask:0xf
	v_fmac_f32_dpp v33, v33, v92 row_newbcast:12 row_mask:0xf bank_mask:0xf
	v_fmac_f32_dpp v30, v30, v93 row_newbcast:13 row_mask:0xf bank_mask:0xf
	v_fmac_f32_dpp v31, v31, v93 row_newbcast:13 row_mask:0xf bank_mask:0xf
	v_fmac_f32_dpp v32, v32, v93 row_newbcast:13 row_mask:0xf bank_mask:0xf
	v_fmac_f32_dpp v33, v33, v93 row_newbcast:13 row_mask:0xf bank_mask:0xf
	v_fmac_f32_dpp v30, v30, v94 row_newbcast:14 row_mask:0xf bank_mask:0xf
	v_fmac_f32_dpp v31, v31, v94 row_newbcast:14 row_mask:0xf bank_mask:0xf
	v_fmac_f32_dpp v32, v32, v94 row_newbcast:14 row_mask:0xf bank_mask:0xf
	v_fmac_f32_dpp v33, v33, v94 row_newbcast:14 row_mask:0xf bank_mask:0xf
	v_cvt_pk_bf16_f32 v80, v30, v31
	v_cvt_pk_bf16_f32 v81, v32, v33
	ds_write_b16 v96, v80 offset:5120
	ds_write_b16_d16_hi v96, v80 offset:5200
	ds_write_b16 v96, v81 offset:5280
	ds_write_b16_d16_hi v96, v81 offset:5360
	s_setprio 1
